# W_up conversion rebalanced: P1 tail +10240, GLU tail +6144, prologue -16384
# baseline (speedup 1.0000x reference)
.LBB0_49:
	s_and_b64 vcc, exec, s[0:1]
	s_cbranch_vccz .LBB0_55
	s_cmpk_gt_i32 s12, 0x13ff
	s_cbranch_scc1 .LBB0_55
	s_add_i32 s13, s12, 0x9800
	s_mul_hi_i32 s0, s13, 0x2fa0be83
	s_lshr_b32 s1, s0, 31
	s_ashr_i32 s0, s0, 7
	v_readlane_b32 s16, v243, 33
	s_add_i32 s0, s0, s1
	v_lshrrev_b32_e32 v1, 3, v174
	v_readlane_b32 s26, v243, 43
	v_readlane_b32 s27, v243, 44
	s_mul_i32 s1, s0, 0x2b0
	s_waitcnt vmcnt(10)
	v_lshl_or_b32 v4, s0, 6, v1
	s_mov_b32 s2, 0x15800
	v_mov_b64_e32 v[2:3], s[26:27]
	s_sub_i32 s3, s13, s1
	v_mad_i64_i32 v[2:3], s[0:1], v4, s2, v[2:3]
	s_lshl_b32 s0, s3, 5
	v_and_b32_e32 v35, 7, v0
	s_ashr_i32 s1, s0, 31
	v_lshl_add_u64 v[2:3], s[0:1], 2, v[2:3]
	v_mov_b32_e32 v67, 0
	v_lshlrev_b32_e32 v66, 4, v35
	s_waitcnt vmcnt(4)
	v_lshl_add_u64 v[26:27], v[2:3], 0, v[66:67]
	s_mov_b32 s3, 0xac000
	v_add_co_u32_e32 v2, vcc, s3, v26
	s_mov_b32 s4, 0x158000
	s_nop 0
	v_addc_co_u32_e32 v3, vcc, 0, v27, vcc
	v_add_co_u32_e32 v10, vcc, s4, v26
	s_mov_b32 s5, 0x204000
	s_nop 0
	v_addc_co_u32_e32 v11, vcc, 0, v27, vcc
	v_add_co_u32_e32 v12, vcc, s5, v26
	s_mov_b32 s6, 0x2b0000
	s_nop 0
	v_addc_co_u32_e32 v13, vcc, 0, v27, vcc
	v_add_co_u32_e32 v18, vcc, s6, v26
	s_mov_b32 s7, 0x35c000
	s_nop 0
	v_addc_co_u32_e32 v19, vcc, 0, v27, vcc
	v_add_co_u32_e32 v20, vcc, s7, v26
	s_mov_b32 s8, 0x408000
	s_nop 0
	v_addc_co_u32_e32 v21, vcc, 0, v27, vcc
	v_add_co_u32_e32 v28, vcc, s8, v26
	s_mov_b32 s9, 0x4b4000
	s_nop 0
	v_addc_co_u32_e32 v29, vcc, 0, v27, vcc
	global_load_dwordx4 v[6:9], v[26:27], off nt
	s_nop 0
	global_load_dwordx4 v[2:5], v[2:3], off nt
	v_add_co_u32_e32 v26, vcc, s9, v26
	global_load_dwordx4 v[14:17], v[10:11], off nt
	s_nop 0
	global_load_dwordx4 v[10:13], v[12:13], off nt
	v_addc_co_u32_e32 v27, vcc, 0, v27, vcc
	global_load_dwordx4 v[22:25], v[18:19], off nt
	s_nop 0
	global_load_dwordx4 v[18:21], v[20:21], off nt
	s_nop 0
	global_load_dwordx4 v[30:33], v[28:29], off nt
	s_nop 0
	global_load_dwordx4 v[26:29], v[26:27], off nt
	s_lshl_b32 s0, s84, 14
	s_add_i32 s15, s0, 0
	v_lshl_add_u64 v[36:37], s[80:81], 0, v[66:67]
	s_mov_b64 s[0:1], 0x1800000
	v_lshlrev_b32_e32 v34, 2, v35
	v_add_u32_e32 v38, s15, v66
	v_mul_u32_u24_e32 v35, 0x420, v35
	v_lshl_add_u64 v[68:69], v[36:37], 0, s[0:1]
	v_mul_u32_u24_e32 v36, 0x84, v1
	v_lshlrev_b32_e32 v37, 2, v1
	v_or_b32_e32 v70, 8, v1
	v_or_b32_e32 v71, 16, v1
	v_or_b32_e32 v72, 24, v1
	v_add3_u32 v73, s15, v35, v37
	v_lshlrev_b32_e32 v66, 2, v34
	v_add_u32_e32 v74, v38, v36
	v_readlane_b32 s17, v243, 34
	v_readlane_b32 s18, v243, 35
	v_readlane_b32 s19, v243, 36
	v_readlane_b32 s20, v243, 37
	v_readlane_b32 s21, v243, 38
	v_readlane_b32 s22, v243, 39
	v_readlane_b32 s23, v243, 40
	v_readlane_b32 s24, v243, 41
	v_readlane_b32 s25, v243, 42
	v_readlane_b32 s28, v243, 45
	v_readlane_b32 s29, v243, 46
	v_readlane_b32 s30, v243, 47
	v_readlane_b32 s31, v243, 48
	s_branch .LBB0_53

.LBB0_178:
	v_readlane_b32 s8, v243, 49
	v_readlane_b32 s11, v243, 52
	s_bitcmp1_b32 s11, 11
	s_cselect_b64 s[2:3], -1, 0
	s_or_b64 s[0:1], s[2:3], s[0:1]
	s_and_b64 vcc, exec, s[0:1]
	v_readlane_b32 s9, v243, 50
	v_readlane_b32 s10, v243, 51
	s_cbranch_vccnz .LBB0_184
	s_lshl_b32 s0, s94, 3
	s_add_i32 s0, s0, s84
	s_add_i32 s12, s0, 0xfffffae0
	s_cmpk_gt_i32 s12, 0x47ff
	s_cbranch_scc1 .LBB0_184
	s_mul_hi_i32 s0, s12, 0x2fa0be83
	s_lshr_b32 s1, s0, 31
	s_ashr_i32 s0, s0, 7
	v_readlane_b32 s16, v243, 33
	s_add_i32 s0, s0, s1
	v_lshrrev_b32_e32 v1, 3, v174
	v_readlane_b32 s26, v243, 43
	v_readlane_b32 s27, v243, 44
	s_mul_i32 s1, s0, 0x2b0
	s_waitcnt vmcnt(0)
	v_lshl_or_b32 v4, s0, 6, v1
	s_mov_b32 s2, 0x15800
	v_mov_b64_e32 v[2:3], s[26:27]
	s_sub_i32 s3, s12, s1
	v_mad_i64_i32 v[2:3], s[0:1], v4, s2, v[2:3]
	s_lshl_b32 s0, s3, 5
	v_and_b32_e32 v35, 7, v0
	s_ashr_i32 s1, s0, 31
	v_lshl_add_u64 v[2:3], s[0:1], 2, v[2:3]
	v_mov_b32_e32 v67, 0
	v_lshlrev_b32_e32 v66, 4, v35
	v_lshl_add_u64 v[26:27], v[2:3], 0, v[66:67]
	s_mov_b32 s3, 0xac000
	v_add_co_u32_e32 v2, vcc, s3, v26
	s_mov_b32 s4, 0x158000
	s_nop 0
	v_addc_co_u32_e32 v3, vcc, 0, v27, vcc
	v_add_co_u32_e32 v10, vcc, s4, v26
	s_mov_b32 s5, 0x204000
	s_nop 0
	v_addc_co_u32_e32 v11, vcc, 0, v27, vcc
	v_add_co_u32_e32 v12, vcc, s5, v26
	s_mov_b32 s8, 0x2b0000
	s_nop 0
	v_addc_co_u32_e32 v13, vcc, 0, v27, vcc
	v_add_co_u32_e32 v18, vcc, s8, v26
	s_mov_b32 s9, 0x35c000
	s_nop 0
	v_addc_co_u32_e32 v19, vcc, 0, v27, vcc
	v_add_co_u32_e32 v20, vcc, s9, v26
	s_mov_b32 s10, 0x408000
	s_nop 0
	v_addc_co_u32_e32 v21, vcc, 0, v27, vcc
	v_add_co_u32_e32 v28, vcc, s10, v26
	s_mov_b32 s11, 0x4b4000
	s_nop 0
	v_addc_co_u32_e32 v29, vcc, 0, v27, vcc
	global_load_dwordx4 v[6:9], v[26:27], off nt
	s_nop 0
	global_load_dwordx4 v[2:5], v[2:3], off nt
	v_add_co_u32_e32 v26, vcc, s11, v26
	global_load_dwordx4 v[14:17], v[10:11], off nt
	s_nop 0
	global_load_dwordx4 v[10:13], v[12:13], off nt
	v_addc_co_u32_e32 v27, vcc, 0, v27, vcc
	global_load_dwordx4 v[22:25], v[18:19], off nt
	s_nop 0
	global_load_dwordx4 v[18:21], v[20:21], off nt
	s_nop 0
	global_load_dwordx4 v[30:33], v[28:29], off nt
	s_nop 0
	global_load_dwordx4 v[26:29], v[26:27], off nt
	s_lshl_b32 s0, s84, 14
	s_add_i32 s13, s0, 0
	v_lshl_add_u64 v[36:37], s[80:81], 0, v[66:67]
	s_mov_b64 s[0:1], 0x1800000
	v_lshlrev_b32_e32 v34, 2, v35
	v_add_u32_e32 v38, s13, v66
	v_mul_u32_u24_e32 v35, 0x420, v35
	v_lshl_add_u64 v[68:69], v[36:37], 0, s[0:1]
	v_mul_u32_u24_e32 v36, 0x84, v1
	v_lshlrev_b32_e32 v37, 2, v1
	v_or_b32_e32 v70, 8, v1
	v_or_b32_e32 v71, 16, v1
	v_or_b32_e32 v72, 24, v1
	v_add3_u32 v73, s13, v35, v37
	v_lshl_or_b32 v75, s12, 5, v1
	v_lshlrev_b32_e32 v66, 2, v34
	v_add_u32_e32 v74, v38, v36
	v_readlane_b32 s17, v243, 34
	v_readlane_b32 s18, v243, 35
	v_readlane_b32 s19, v243, 36
	v_readlane_b32 s20, v243, 37
	v_readlane_b32 s21, v243, 38
	v_readlane_b32 s22, v243, 39
	v_readlane_b32 s23, v243, 40
	v_readlane_b32 s24, v243, 41
	v_readlane_b32 s25, v243, 42
	v_readlane_b32 s28, v243, 45
	v_readlane_b32 s29, v243, 46
	v_readlane_b32 s30, v243, 47
	v_readlane_b32 s31, v243, 48
	s_branch .LBB0_182
.LBB0_181:
	s_add_i32 s14, s12, 0x5c0
	s_cmpk_gt_i32 s12, 0x423f
	s_cselect_b64 s[0:1], -1, 0
	s_cmpk_lt_i32 s12, 0x4240
	s_cselect_b32 s12, s14, s13
	s_mul_hi_i32 s15, s12, 0x2fa0be83
	s_lshr_b32 s16, s15, 31
	s_ashr_i32 s15, s15, 7
	s_add_i32 s15, s15, s16
	s_mul_i32 s16, s15, 0x2b0
	v_lshl_or_b32 v4, s15, 6, v1
	v_mov_b64_e32 v[2:3], s[46:47]
	s_sub_i32 s12, s12, s16
	v_mad_i64_i32 v[2:3], s[16:17], v4, s2, v[2:3]
	s_lshl_b32 s16, s12, 5
	s_ashr_i32 s17, s16, 31
	v_lshl_add_u64 v[2:3], s[16:17], 2, v[2:3]
	v_lshl_add_u64 v[26:27], v[2:3], 0, v[66:67]
	v_add_co_u32_e32 v2, vcc, s3, v26
	s_mul_hi_i32 s12, s13, 0x2fa0be83
	s_nop 0
	v_addc_co_u32_e32 v3, vcc, 0, v27, vcc
	v_add_co_u32_e32 v10, vcc, s4, v26
	global_load_dwordx4 v[6:9], v[26:27], off nt
	s_nop 0
	global_load_dwordx4 v[2:5], v[2:3], off nt
	v_addc_co_u32_e32 v11, vcc, 0, v27, vcc
	v_add_co_u32_e32 v12, vcc, s5, v26
	s_lshr_b32 s15, s12, 31
	s_nop 0
	v_addc_co_u32_e32 v13, vcc, 0, v27, vcc
	v_add_co_u32_e32 v18, vcc, s8, v26
	global_load_dwordx4 v[14:17], v[10:11], off nt
	s_nop 0
	global_load_dwordx4 v[10:13], v[12:13], off nt
	v_addc_co_u32_e32 v19, vcc, 0, v27, vcc
	v_add_co_u32_e32 v20, vcc, s9, v26
	s_ashr_i32 s12, s12, 7
	s_nop 0
	v_addc_co_u32_e32 v21, vcc, 0, v27, vcc
	v_add_co_u32_e32 v28, vcc, s10, v26
	global_load_dwordx4 v[22:25], v[18:19], off nt
	s_nop 0
	global_load_dwordx4 v[18:21], v[20:21], off nt
	v_addc_co_u32_e32 v29, vcc, 0, v27, vcc
	v_add_co_u32_e32 v26, vcc, s11, v26
	s_add_i32 s12, s12, s15
	s_nop 0
	v_addc_co_u32_e32 v27, vcc, 0, v27, vcc
	global_load_dwordx4 v[30:33], v[28:29], off nt
	s_nop 0
	global_load_dwordx4 v[26:29], v[26:27], off nt
	s_waitcnt vmcnt(19)
	ds_write2_b32 v74, v34, v35 offset1:1
	ds_write2_b32 v74, v36, v37 offset0:2 offset1:3
	s_waitcnt vmcnt(18)
	ds_write2_b32 v76, v38, v39 offset1:1
	ds_write2_b32 v77, v40, v41 offset1:1
	s_waitcnt vmcnt(17)
	ds_write2_b32 v78, v42, v43 offset1:1
	ds_write2_b32 v79, v44, v45 offset1:1
	s_waitcnt vmcnt(16)
	ds_write2_b32 v80, v46, v47 offset1:1
	ds_write2_b32 v81, v48, v49 offset1:1
	s_waitcnt vmcnt(15)
	ds_write2_b32 v82, v50, v51 offset1:1
	ds_write2_b32 v83, v52, v53 offset1:1
	s_waitcnt vmcnt(14)
	ds_write2_b32 v84, v54, v55 offset1:1
	ds_write2_b32 v85, v56, v57 offset1:1
	s_waitcnt vmcnt(13)
	ds_write2_b32 v86, v58, v59 offset1:1
	ds_write2_b32 v87, v60, v61 offset1:1
	s_waitcnt vmcnt(12)
	ds_write2_b32 v88, v62, v63 offset1:1
	ds_write2_b32 v89, v64, v65 offset1:1
	s_waitcnt lgkmcnt(0)
	s_mul_i32 s15, s12, 0x2b0
	s_sub_i32 s13, s13, s15
	ds_read2_b32 v[38:39], v73 offset0:33 offset1:41
	ds_read2_b32 v[40:41], v73 offset1:8
	ds_read2_b32 v[42:43], v73 offset0:66 offset1:74
	ds_read2_b32 v[44:45], v73 offset0:99 offset1:107
	ds_read2_b32 v[46:47], v73 offset0:132 offset1:140
	ds_read2_b32 v[48:49], v73 offset0:165 offset1:173
	ds_read2_b32 v[50:51], v73 offset0:198 offset1:206
	ds_read2_b32 v[52:53], v73 offset0:231 offset1:239
	s_lshl_b32 s15, s13, 5
	s_lshl_b32 s12, s12, 6
	v_or_b32_e32 v56, s15, v1
	s_ashr_i32 s13, s12, 31
	v_ashrrev_i32_e32 v57, 31, v56
	v_lshl_add_u64 v[54:55], s[12:13], 1, v[68:69]
	v_lshlrev_b64 v[56:57], 13, v[56:57]
	s_waitcnt lgkmcnt(6)
	v_cvt_pk_bf16_f32 v34, v40, v38
	s_waitcnt lgkmcnt(4)
	v_cvt_pk_bf16_f32 v35, v42, v44
	s_waitcnt lgkmcnt(2)
	v_cvt_pk_bf16_f32 v36, v46, v48
	s_waitcnt lgkmcnt(0)
	v_cvt_pk_bf16_f32 v37, v50, v52
	v_lshl_add_u64 v[56:57], v[54:55], 0, v[56:57]
	v_or_b32_e32 v38, s15, v70
	global_store_dwordx4 v[56:57], v[34:37], off nt
	v_add_u32_e32 v75, 0xb800, v75
	s_mov_b32 s12, s14
	v_cvt_pk_bf16_f32 v34, v41, v39
	v_ashrrev_i32_e32 v39, 31, v38
	v_cvt_pk_bf16_f32 v35, v43, v45
	v_cvt_pk_bf16_f32 v36, v47, v49
	v_cvt_pk_bf16_f32 v37, v51, v53
	v_lshlrev_b64 v[38:39], 13, v[38:39]
	ds_read2_b32 v[40:41], v73 offset0:49 offset1:57
	ds_read2_b32 v[42:43], v73 offset0:16 offset1:24
	ds_read2_b32 v[44:45], v73 offset0:82 offset1:90
	ds_read2_b32 v[46:47], v73 offset0:115 offset1:123
	ds_read2_b32 v[48:49], v73 offset0:148 offset1:156
	ds_read2_b32 v[50:51], v73 offset0:181 offset1:189
	ds_read2_b32 v[52:53], v73 offset0:214 offset1:222
	ds_read2_b32 v[56:57], v73 offset0:247 offset1:255
	v_lshl_add_u64 v[38:39], v[54:55], 0, v[38:39]
	global_store_dwordx4 v[38:39], v[34:37], off nt
	v_or_b32_e32 v38, s15, v71
	v_ashrrev_i32_e32 v39, 31, v38
	v_lshlrev_b64 v[38:39], 13, v[38:39]
	s_waitcnt lgkmcnt(6)
	v_cvt_pk_bf16_f32 v34, v42, v40
	s_waitcnt lgkmcnt(4)
	v_cvt_pk_bf16_f32 v35, v44, v46
	s_waitcnt lgkmcnt(2)
	v_cvt_pk_bf16_f32 v36, v48, v50
	s_waitcnt lgkmcnt(0)
	v_cvt_pk_bf16_f32 v37, v52, v56
	v_lshl_add_u64 v[38:39], v[54:55], 0, v[38:39]
	global_store_dwordx4 v[38:39], v[34:37], off nt
	v_or_b32_e32 v38, s15, v72
	v_ashrrev_i32_e32 v39, 31, v38
	v_lshlrev_b64 v[38:39], 13, v[38:39]
	v_cvt_pk_bf16_f32 v34, v43, v41
	v_cvt_pk_bf16_f32 v35, v45, v47
	v_cvt_pk_bf16_f32 v36, v49, v51
	v_cvt_pk_bf16_f32 v37, v53, v57
	v_lshl_add_u64 v[38:39], v[54:55], 0, v[38:39]
	global_store_dwordx4 v[38:39], v[34:37], off nt
	s_waitcnt lgkmcnt(0)
	s_andn2_b64 vcc, exec, s[0:1]
	s_cbranch_vccz .LBB0_184
.LBB0_182:
	s_add_i32 s13, s12, 0x2e0
	s_cmpk_lt_i32 s12, 0x4520
	s_cselect_b32 s0, s13, s12
	s_mul_hi_i32 s1, s0, 0x2fa0be83
	s_lshr_b32 s14, s1, 31
	s_ashr_i32 s1, s1, 7
	s_add_i32 s16, s1, s14
	s_mul_i32 s1, s16, 0x2b0
	v_readlane_b32 s36, v243, 33
	s_sub_i32 s0, s0, s1
	v_readlane_b32 s46, v243, 43
	v_readlane_b32 s47, v243, 44
	s_lshl_b32 s14, s0, 5
	s_waitcnt vmcnt(11)
	v_lshl_or_b32 v36, s16, 6, v1
	v_mov_b64_e32 v[34:35], s[46:47]
	s_ashr_i32 s15, s14, 31
	v_mad_i64_i32 v[34:35], s[16:17], v36, s2, v[34:35]
	v_lshl_add_u64 v[34:35], s[14:15], 2, v[34:35]
	s_waitcnt vmcnt(5)
	v_lshl_add_u64 v[58:59], v[34:35], 0, v[66:67]
	v_add_co_u32_e32 v38, vcc, s3, v58
	v_add_u32_e32 v76, 0x420, v74
	s_nop 0
	v_addc_co_u32_e32 v39, vcc, 0, v59, vcc
	v_add_co_u32_e32 v42, vcc, s4, v58
	global_load_dwordx4 v[34:37], v[58:59], off nt
	s_nop 0
	global_load_dwordx4 v[38:41], v[38:39], off nt
	v_addc_co_u32_e32 v43, vcc, 0, v59, vcc
	v_add_co_u32_e32 v46, vcc, s5, v58
	v_add_u32_e32 v77, 0x428, v74
	s_nop 0
	v_addc_co_u32_e32 v47, vcc, 0, v59, vcc
	v_add_co_u32_e32 v50, vcc, s8, v58
	global_load_dwordx4 v[42:45], v[42:43], off nt
	s_nop 0
	global_load_dwordx4 v[46:49], v[46:47], off nt
	v_addc_co_u32_e32 v51, vcc, 0, v59, vcc
	v_add_co_u32_e32 v54, vcc, s9, v58
	v_add_u32_e32 v78, 0x840, v74
	s_nop 0
	v_addc_co_u32_e32 v55, vcc, 0, v59, vcc
	v_add_co_u32_e32 v60, vcc, s10, v58
	global_load_dwordx4 v[50:53], v[50:51], off nt
	s_nop 0
	global_load_dwordx4 v[54:57], v[54:55], off nt
	v_addc_co_u32_e32 v61, vcc, 0, v59, vcc
	s_waitcnt vmcnt(10)
	v_add_co_u32_e32 v62, vcc, s11, v58
	v_add_u32_e32 v79, 0x848, v74
	s_nop 0
	v_addc_co_u32_e32 v63, vcc, 0, v59, vcc
	global_load_dwordx4 v[58:61], v[60:61], off nt
	s_nop 0
	global_load_dwordx4 v[62:65], v[62:63], off nt
	v_add_u32_e32 v80, 0xc60, v74
	v_add_u32_e32 v81, 0xc68, v74
	v_add_u32_e32 v82, 0x1080, v74
	v_add_u32_e32 v83, 0x1088, v74
	v_add_u32_e32 v84, 0x14a0, v74
	v_add_u32_e32 v85, 0x14a8, v74
	v_add_u32_e32 v86, 0x18c0, v74
	v_add_u32_e32 v87, 0x18c8, v74
	v_add_u32_e32 v88, 0x1ce0, v74
	v_add_u32_e32 v89, 0x1ce8, v74
	s_waitcnt vmcnt(15)
	ds_write2_b32 v74, v6, v7 offset1:1
	ds_write2_b32 v74, v8, v9 offset0:2 offset1:3
	s_waitcnt vmcnt(14)
	ds_write2_b32 v76, v2, v3 offset1:1
	ds_write2_b32 v77, v4, v5 offset1:1
	s_waitcnt vmcnt(13)
	ds_write2_b32 v78, v14, v15 offset1:1
	ds_write2_b32 v79, v16, v17 offset1:1
	s_waitcnt vmcnt(12)
	ds_write2_b32 v80, v10, v11 offset1:1
	ds_write2_b32 v81, v12, v13 offset1:1
	s_waitcnt vmcnt(11)
	ds_write2_b32 v82, v22, v23 offset1:1
	ds_write2_b32 v83, v24, v25 offset1:1
	s_waitcnt vmcnt(10)
	ds_write2_b32 v84, v18, v19 offset1:1
	ds_write2_b32 v85, v20, v21 offset1:1
	s_waitcnt vmcnt(9)
	ds_write2_b32 v86, v30, v31 offset1:1
	ds_write2_b32 v87, v32, v33 offset1:1
	s_waitcnt vmcnt(8)
	ds_write2_b32 v88, v26, v27 offset1:1
	ds_write2_b32 v89, v28, v29 offset1:1
	s_mul_hi_i32 s0, s12, 0x2fa0be83
	s_waitcnt lgkmcnt(0)
	s_lshr_b32 s1, s0, 31
	s_ashr_i32 s0, s0, 7
	s_add_i32 s18, s0, s1
	ds_read2_b32 v[6:7], v73 offset0:33 offset1:41
	ds_read2_b32 v[8:9], v73 offset1:8
	ds_read2_b32 v[10:11], v73 offset0:66 offset1:74
	ds_read2_b32 v[12:13], v73 offset0:99 offset1:107
	ds_read2_b32 v[14:15], v73 offset0:132 offset1:140
	ds_read2_b32 v[16:17], v73 offset0:165 offset1:173
	ds_read2_b32 v[18:19], v73 offset0:198 offset1:206
	ds_read2_b32 v[20:21], v73 offset0:231 offset1:239
	s_lshl_b32 s0, s18, 6
	s_mulk_i32 s18, 0xaa00
	v_add_u32_e32 v24, s18, v75
	s_ashr_i32 s1, s0, 31
	v_ashrrev_i32_e32 v25, 31, v24
	v_lshl_add_u64 v[22:23], s[0:1], 1, v[68:69]
	v_lshlrev_b64 v[26:27], 13, v[24:25]
	s_waitcnt lgkmcnt(0)
	v_cvt_pk_bf16_f32 v2, v8, v6
	v_cvt_pk_bf16_f32 v3, v10, v12
	v_cvt_pk_bf16_f32 v4, v14, v16
	v_cvt_pk_bf16_f32 v5, v18, v20
	v_lshl_add_u64 v[26:27], v[22:23], 0, v[26:27]
	v_add_u32_e32 v6, 8, v24
	global_store_dwordx4 v[26:27], v[2:5], off nt
	s_cmpk_gt_i32 s12, 0x451f
	v_readlane_b32 s37, v243, 34
	v_cvt_pk_bf16_f32 v2, v9, v7
	v_ashrrev_i32_e32 v7, 31, v6
	v_cvt_pk_bf16_f32 v3, v11, v13
	v_cvt_pk_bf16_f32 v4, v15, v17
	v_cvt_pk_bf16_f32 v5, v19, v21
	v_lshlrev_b64 v[6:7], 13, v[6:7]
	ds_read2_b32 v[8:9], v73 offset0:49 offset1:57
	ds_read2_b32 v[10:11], v73 offset0:16 offset1:24
	ds_read2_b32 v[12:13], v73 offset0:82 offset1:90
	ds_read2_b32 v[14:15], v73 offset0:115 offset1:123
	ds_read2_b32 v[16:17], v73 offset0:148 offset1:156
	ds_read2_b32 v[18:19], v73 offset0:181 offset1:189
	ds_read2_b32 v[20:21], v73 offset0:214 offset1:222
	ds_read2_b32 v[26:27], v73 offset0:247 offset1:255
	v_lshl_add_u64 v[6:7], v[22:23], 0, v[6:7]
	global_store_dwordx4 v[6:7], v[2:5], off nt
	v_add_u32_e32 v6, 16, v24
	v_ashrrev_i32_e32 v7, 31, v6
	v_lshlrev_b64 v[6:7], 13, v[6:7]
	s_waitcnt lgkmcnt(6)
	v_cvt_pk_bf16_f32 v2, v10, v8
	s_waitcnt lgkmcnt(4)
	v_cvt_pk_bf16_f32 v3, v12, v14
	s_waitcnt lgkmcnt(2)
	v_cvt_pk_bf16_f32 v4, v16, v18
	s_waitcnt lgkmcnt(0)
	v_cvt_pk_bf16_f32 v5, v20, v26
	v_lshl_add_u64 v[6:7], v[22:23], 0, v[6:7]
	global_store_dwordx4 v[6:7], v[2:5], off nt
	v_add_u32_e32 v6, 24, v24
	v_ashrrev_i32_e32 v7, 31, v6
	v_lshlrev_b64 v[6:7], 13, v[6:7]
	v_cvt_pk_bf16_f32 v2, v11, v9
	v_cvt_pk_bf16_f32 v3, v13, v15
	v_cvt_pk_bf16_f32 v4, v17, v19
	v_cvt_pk_bf16_f32 v5, v21, v27
	v_lshl_add_u64 v[6:7], v[22:23], 0, v[6:7]
	global_store_dwordx4 v[6:7], v[2:5], off nt
	s_waitcnt lgkmcnt(0)
	v_readlane_b32 s38, v243, 35
	v_readlane_b32 s39, v243, 36
	v_readlane_b32 s40, v243, 37
	v_readlane_b32 s41, v243, 38
	v_readlane_b32 s42, v243, 39
	v_readlane_b32 s43, v243, 40
	v_readlane_b32 s44, v243, 41
	v_readlane_b32 s45, v243, 42
	v_readlane_b32 s48, v243, 45
	v_readlane_b32 s49, v243, 46
	v_readlane_b32 s50, v243, 47
	v_readlane_b32 s51, v243, 48
	s_cbranch_scc0 .LBB0_181

.LBB0_513:
	v_readlane_b32 s2, v243, 0
	s_cmpk_eq_i32 s2, 0x100
	s_cselect_b64 s[0:1], -1, 0
	s_cmpk_lg_i32 s2, 0x100
	s_cselect_b64 s[2:3], -1, 0
	s_bitcmp1_b32 s91, 5
	s_cselect_b64 s[6:7], -1, 0
	s_or_b64 s[2:3], s[2:3], s[6:7]
	s_cmp_lt_i32 s94, 32
	s_cselect_b64 s[6:7], -1, 0
	s_or_b64 s[2:3], s[6:7], s[2:3]
	s_and_b64 vcc, exec, s[2:3]
	s_cbranch_vccnz .LBB0_519
	s_lshl_b32 s2, s94, 3
	s_add_i32 s2, s2, s84
	s_add_i32 s14, s2, 0x4700
	s_cmp_gt_i32 s14, 0x97ff
	s_cbranch_scc1 .LBB0_519
	s_mul_hi_i32 s2, s14, 0x2fa0be83
	s_lshr_b32 s3, s2, 31
	s_ashr_i32 s2, s2, 7
	v_readlane_b32 s16, v243, 33
	s_add_i32 s2, s2, s3
	v_lshrrev_b32_e32 v1, 3, v174
	v_readlane_b32 s26, v243, 43
	v_readlane_b32 s27, v243, 44
	s_mul_i32 s3, s2, 0x2b0
	s_waitcnt vmcnt(0)
	v_lshl_or_b32 v4, s2, 6, v1
	s_mov_b32 s6, 0x15800
	v_mov_b64_e32 v[2:3], s[26:27]
	s_sub_i32 s7, s14, s3
	v_mad_i64_i32 v[2:3], s[2:3], v4, s6, v[2:3]
	s_lshl_b32 s2, s7, 5
	v_and_b32_e32 v35, 7, v0
	s_ashr_i32 s3, s2, 31
	v_lshl_add_u64 v[2:3], s[2:3], 2, v[2:3]
	v_mov_b32_e32 v67, 0
	v_lshlrev_b32_e32 v66, 4, v35
	v_lshl_add_u64 v[26:27], v[2:3], 0, v[66:67]
	s_mov_b32 s7, 0xac000
	v_add_co_u32_e32 v10, vcc, s7, v26
	s_mov_b32 s8, 0x158000
	s_nop 0
	v_addc_co_u32_e32 v11, vcc, 0, v27, vcc
	global_load_dwordx4 v[6:9], v[26:27], off nt
	global_load_dwordx4 v[2:5], v[10:11], off nt
	v_add_co_u32_e32 v10, vcc, s8, v26
	s_mov_b32 s9, 0x204000
	s_nop 0
	v_addc_co_u32_e32 v11, vcc, 0, v27, vcc
	v_add_co_u32_e32 v12, vcc, s9, v26
	s_mov_b32 s10, 0x2b0000
	s_nop 0
	v_addc_co_u32_e32 v13, vcc, 0, v27, vcc
	v_add_co_u32_e32 v18, vcc, s10, v26
	s_mov_b32 s11, 0x35c000
	s_nop 0
	v_addc_co_u32_e32 v19, vcc, 0, v27, vcc
	v_add_co_u32_e32 v20, vcc, s11, v26
	s_mov_b32 s12, 0x408000
	s_nop 0
	v_addc_co_u32_e32 v21, vcc, 0, v27, vcc
	v_add_co_u32_e32 v28, vcc, s12, v26
	s_mov_b32 s13, 0x4b4000
	s_nop 0
	v_addc_co_u32_e32 v29, vcc, 0, v27, vcc
	v_add_co_u32_e32 v26, vcc, s13, v26
	global_load_dwordx4 v[14:17], v[10:11], off nt
	s_nop 0
	global_load_dwordx4 v[10:13], v[12:13], off nt
	v_addc_co_u32_e32 v27, vcc, 0, v27, vcc
	global_load_dwordx4 v[22:25], v[18:19], off nt
	s_nop 0
	global_load_dwordx4 v[18:21], v[20:21], off nt
	s_nop 0
	global_load_dwordx4 v[30:33], v[28:29], off nt
	s_nop 0
	global_load_dwordx4 v[26:29], v[26:27], off nt
	s_lshl_b32 s2, s84, 14
	s_add_i32 s15, s2, 0
	v_lshl_add_u64 v[36:37], s[80:81], 0, v[66:67]
	s_mov_b64 s[2:3], 0x1800000
	v_lshlrev_b32_e32 v34, 2, v35
	v_add_u32_e32 v38, s15, v66
	v_mul_u32_u24_e32 v35, 0x420, v35
	v_lshl_add_u64 v[68:69], v[36:37], 0, s[2:3]
	v_mul_u32_u24_e32 v36, 0x84, v1
	v_lshlrev_b32_e32 v37, 2, v1
	v_or_b32_e32 v70, 8, v1
	v_or_b32_e32 v71, 16, v1
	v_or_b32_e32 v72, 24, v1
	v_add3_u32 v73, s15, v35, v37
	v_lshl_or_b32 v75, s14, 5, v1
	v_lshlrev_b32_e32 v66, 2, v34
	v_add_u32_e32 v74, v38, v36
	v_readlane_b32 s17, v243, 34
	v_readlane_b32 s18, v243, 35
	v_readlane_b32 s19, v243, 36
	v_readlane_b32 s20, v243, 37
	v_readlane_b32 s21, v243, 38
	v_readlane_b32 s22, v243, 39
	v_readlane_b32 s23, v243, 40
	v_readlane_b32 s24, v243, 41
	v_readlane_b32 s25, v243, 42
	v_readlane_b32 s28, v243, 45
	v_readlane_b32 s29, v243, 46
	v_readlane_b32 s30, v243, 47
	v_readlane_b32 s31, v243, 48
	s_branch .LBB0_517
.LBB0_516:
	s_add_i32 s16, s14, 0xe00
	s_cmp_gt_i32 s14, 0x89ff
	s_cselect_b64 s[2:3], -1, 0
	s_cmp_lt_i32 s14, 0x8a00
	s_cselect_b32 s14, s16, s15
	s_mul_hi_i32 s17, s14, 0x2fa0be83
	s_lshr_b32 s18, s17, 31
	s_ashr_i32 s17, s17, 7
	s_add_i32 s17, s17, s18
	s_mul_i32 s18, s17, 0x2b0
	v_lshl_or_b32 v4, s17, 6, v1
	v_mov_b64_e32 v[2:3], s[46:47]
	s_sub_i32 s14, s14, s18
	v_mad_i64_i32 v[2:3], s[18:19], v4, s6, v[2:3]
	s_lshl_b32 s18, s14, 5
	s_ashr_i32 s19, s18, 31
	v_lshl_add_u64 v[2:3], s[18:19], 2, v[2:3]
	v_lshl_add_u64 v[26:27], v[2:3], 0, v[66:67]
	v_add_co_u32_e32 v2, vcc, s7, v26
	s_mul_hi_i32 s14, s15, 0x2fa0be83
	s_nop 0
	v_addc_co_u32_e32 v3, vcc, 0, v27, vcc
	v_add_co_u32_e32 v10, vcc, s8, v26
	global_load_dwordx4 v[6:9], v[26:27], off nt
	s_nop 0
	global_load_dwordx4 v[2:5], v[2:3], off nt
	v_addc_co_u32_e32 v11, vcc, 0, v27, vcc
	v_add_co_u32_e32 v12, vcc, s9, v26
	s_lshr_b32 s17, s14, 31
	s_nop 0
	v_addc_co_u32_e32 v13, vcc, 0, v27, vcc
	v_add_co_u32_e32 v18, vcc, s10, v26
	global_load_dwordx4 v[14:17], v[10:11], off nt
	s_nop 0
	global_load_dwordx4 v[10:13], v[12:13], off nt
	v_addc_co_u32_e32 v19, vcc, 0, v27, vcc
	v_add_co_u32_e32 v20, vcc, s11, v26
	s_ashr_i32 s14, s14, 7
	s_nop 0
	v_addc_co_u32_e32 v21, vcc, 0, v27, vcc
	v_add_co_u32_e32 v28, vcc, s12, v26
	global_load_dwordx4 v[22:25], v[18:19], off nt
	s_nop 0
	global_load_dwordx4 v[18:21], v[20:21], off nt
	v_addc_co_u32_e32 v29, vcc, 0, v27, vcc
	v_add_co_u32_e32 v26, vcc, s13, v26
	s_add_i32 s14, s14, s17
	s_nop 0
	v_addc_co_u32_e32 v27, vcc, 0, v27, vcc
	global_load_dwordx4 v[30:33], v[28:29], off nt
	s_nop 0
	global_load_dwordx4 v[26:29], v[26:27], off nt
	s_waitcnt vmcnt(19)
	ds_write2_b32 v74, v34, v35 offset1:1
	ds_write2_b32 v74, v36, v37 offset0:2 offset1:3
	s_waitcnt vmcnt(18)
	ds_write2_b32 v76, v38, v39 offset1:1
	ds_write2_b32 v77, v40, v41 offset1:1
	s_waitcnt vmcnt(17)
	ds_write2_b32 v78, v42, v43 offset1:1
	ds_write2_b32 v79, v44, v45 offset1:1
	s_waitcnt vmcnt(16)
	ds_write2_b32 v80, v46, v47 offset1:1
	ds_write2_b32 v81, v48, v49 offset1:1
	s_waitcnt vmcnt(15)
	ds_write2_b32 v82, v50, v51 offset1:1
	ds_write2_b32 v83, v52, v53 offset1:1
	s_waitcnt vmcnt(14)
	ds_write2_b32 v84, v54, v55 offset1:1
	ds_write2_b32 v85, v56, v57 offset1:1
	s_waitcnt vmcnt(13)
	ds_write2_b32 v86, v58, v59 offset1:1
	ds_write2_b32 v87, v60, v61 offset1:1
	s_waitcnt vmcnt(12)
	ds_write2_b32 v88, v62, v63 offset1:1
	ds_write2_b32 v89, v64, v65 offset1:1
	s_waitcnt lgkmcnt(0)
	s_mul_i32 s17, s14, 0x2b0
	s_sub_i32 s15, s15, s17
	ds_read2_b32 v[38:39], v73 offset0:33 offset1:41
	ds_read2_b32 v[40:41], v73 offset1:8
	ds_read2_b32 v[42:43], v73 offset0:66 offset1:74
	ds_read2_b32 v[44:45], v73 offset0:99 offset1:107
	ds_read2_b32 v[46:47], v73 offset0:132 offset1:140
	ds_read2_b32 v[48:49], v73 offset0:165 offset1:173
	ds_read2_b32 v[50:51], v73 offset0:198 offset1:206
	ds_read2_b32 v[52:53], v73 offset0:231 offset1:239
	s_lshl_b32 s17, s15, 5
	s_lshl_b32 s14, s14, 6
	v_or_b32_e32 v56, s17, v1
	s_ashr_i32 s15, s14, 31
	v_ashrrev_i32_e32 v57, 31, v56
	v_lshl_add_u64 v[54:55], s[14:15], 1, v[68:69]
	v_lshlrev_b64 v[56:57], 13, v[56:57]
	s_waitcnt lgkmcnt(6)
	v_cvt_pk_bf16_f32 v34, v40, v38
	s_waitcnt lgkmcnt(4)
	v_cvt_pk_bf16_f32 v35, v42, v44
	s_waitcnt lgkmcnt(2)
	v_cvt_pk_bf16_f32 v36, v46, v48
	s_waitcnt lgkmcnt(0)
	v_cvt_pk_bf16_f32 v37, v50, v52
	v_lshl_add_u64 v[56:57], v[54:55], 0, v[56:57]
	v_or_b32_e32 v38, s17, v70
	global_store_dwordx4 v[56:57], v[34:37], off nt
	v_add_u32_e32 v75, 0x1c000, v75
	s_mov_b32 s14, s16
	v_cvt_pk_bf16_f32 v34, v41, v39
	v_ashrrev_i32_e32 v39, 31, v38
	v_cvt_pk_bf16_f32 v35, v43, v45
	v_cvt_pk_bf16_f32 v36, v47, v49
	v_cvt_pk_bf16_f32 v37, v51, v53
	v_lshlrev_b64 v[38:39], 13, v[38:39]
	ds_read2_b32 v[40:41], v73 offset0:49 offset1:57
	ds_read2_b32 v[42:43], v73 offset0:16 offset1:24
	ds_read2_b32 v[44:45], v73 offset0:82 offset1:90
	ds_read2_b32 v[46:47], v73 offset0:115 offset1:123
	ds_read2_b32 v[48:49], v73 offset0:148 offset1:156
	ds_read2_b32 v[50:51], v73 offset0:181 offset1:189
	ds_read2_b32 v[52:53], v73 offset0:214 offset1:222
	ds_read2_b32 v[56:57], v73 offset0:247 offset1:255
	v_lshl_add_u64 v[38:39], v[54:55], 0, v[38:39]
	global_store_dwordx4 v[38:39], v[34:37], off nt
	v_or_b32_e32 v38, s17, v71
	v_ashrrev_i32_e32 v39, 31, v38
	v_lshlrev_b64 v[38:39], 13, v[38:39]
	s_waitcnt lgkmcnt(6)
	v_cvt_pk_bf16_f32 v34, v42, v40
	s_waitcnt lgkmcnt(4)
	v_cvt_pk_bf16_f32 v35, v44, v46
	s_waitcnt lgkmcnt(2)
	v_cvt_pk_bf16_f32 v36, v48, v50
	s_waitcnt lgkmcnt(0)
	v_cvt_pk_bf16_f32 v37, v52, v56
	v_lshl_add_u64 v[38:39], v[54:55], 0, v[38:39]
	global_store_dwordx4 v[38:39], v[34:37], off nt
	v_or_b32_e32 v38, s17, v72
	v_ashrrev_i32_e32 v39, 31, v38
	v_lshlrev_b64 v[38:39], 13, v[38:39]
	v_cvt_pk_bf16_f32 v34, v43, v41
	v_cvt_pk_bf16_f32 v35, v45, v47
	v_cvt_pk_bf16_f32 v36, v49, v51
	v_cvt_pk_bf16_f32 v37, v53, v57
	v_lshl_add_u64 v[38:39], v[54:55], 0, v[38:39]
	global_store_dwordx4 v[38:39], v[34:37], off nt
	s_waitcnt lgkmcnt(0)
	s_andn2_b64 vcc, exec, s[2:3]
	s_cbranch_vccz .LBB0_519
.LBB0_517:
	s_add_i32 s15, s14, 0x700
	s_cmp_lt_i32 s14, 0x9100
	s_cselect_b32 s2, s15, s14
	s_mul_hi_i32 s3, s2, 0x2fa0be83
	s_lshr_b32 s16, s3, 31
	s_ashr_i32 s3, s3, 7
	s_add_i32 s18, s3, s16
	s_mul_i32 s3, s18, 0x2b0
	v_readlane_b32 s36, v243, 33
	s_sub_i32 s2, s2, s3
	v_readlane_b32 s46, v243, 43
	v_readlane_b32 s47, v243, 44
	s_lshl_b32 s16, s2, 5
	s_waitcnt vmcnt(11)
	v_lshl_or_b32 v36, s18, 6, v1
	v_mov_b64_e32 v[34:35], s[46:47]
	s_ashr_i32 s17, s16, 31
	v_mad_i64_i32 v[34:35], s[18:19], v36, s6, v[34:35]
	v_lshl_add_u64 v[34:35], s[16:17], 2, v[34:35]
	s_waitcnt vmcnt(5)
	v_lshl_add_u64 v[58:59], v[34:35], 0, v[66:67]
	v_add_co_u32_e32 v38, vcc, s7, v58
	v_add_u32_e32 v76, 0x420, v74
	s_nop 0
	v_addc_co_u32_e32 v39, vcc, 0, v59, vcc
	v_add_co_u32_e32 v42, vcc, s8, v58
	global_load_dwordx4 v[34:37], v[58:59], off nt
	s_nop 0
	global_load_dwordx4 v[38:41], v[38:39], off nt
	v_addc_co_u32_e32 v43, vcc, 0, v59, vcc
	v_add_co_u32_e32 v46, vcc, s9, v58
	v_add_u32_e32 v77, 0x428, v74
	s_nop 0
	v_addc_co_u32_e32 v47, vcc, 0, v59, vcc
	v_add_co_u32_e32 v50, vcc, s10, v58
	global_load_dwordx4 v[42:45], v[42:43], off nt
	s_nop 0
	global_load_dwordx4 v[46:49], v[46:47], off nt
	v_addc_co_u32_e32 v51, vcc, 0, v59, vcc
	v_add_co_u32_e32 v54, vcc, s11, v58
	v_add_u32_e32 v78, 0x840, v74
	s_nop 0
	v_addc_co_u32_e32 v55, vcc, 0, v59, vcc
	v_add_co_u32_e32 v60, vcc, s12, v58
	global_load_dwordx4 v[50:53], v[50:51], off nt
	s_nop 0
	global_load_dwordx4 v[54:57], v[54:55], off nt
	v_addc_co_u32_e32 v61, vcc, 0, v59, vcc
	s_waitcnt vmcnt(10)
	v_add_co_u32_e32 v62, vcc, s13, v58
	v_add_u32_e32 v79, 0x848, v74
	s_nop 0
	v_addc_co_u32_e32 v63, vcc, 0, v59, vcc
	global_load_dwordx4 v[58:61], v[60:61], off nt
	s_nop 0
	global_load_dwordx4 v[62:65], v[62:63], off nt
	v_add_u32_e32 v80, 0xc60, v74
	v_add_u32_e32 v81, 0xc68, v74
	v_add_u32_e32 v82, 0x1080, v74
	v_add_u32_e32 v83, 0x1088, v74
	v_add_u32_e32 v84, 0x14a0, v74
	v_add_u32_e32 v85, 0x14a8, v74
	v_add_u32_e32 v86, 0x18c0, v74
	v_add_u32_e32 v87, 0x18c8, v74
	v_add_u32_e32 v88, 0x1ce0, v74
	v_add_u32_e32 v89, 0x1ce8, v74
	s_waitcnt vmcnt(15)
	ds_write2_b32 v74, v6, v7 offset1:1
	ds_write2_b32 v74, v8, v9 offset0:2 offset1:3
	s_waitcnt vmcnt(14)
	ds_write2_b32 v76, v2, v3 offset1:1
	ds_write2_b32 v77, v4, v5 offset1:1
	s_waitcnt vmcnt(13)
	ds_write2_b32 v78, v14, v15 offset1:1
	ds_write2_b32 v79, v16, v17 offset1:1
	s_waitcnt vmcnt(12)
	ds_write2_b32 v80, v10, v11 offset1:1
	ds_write2_b32 v81, v12, v13 offset1:1
	s_waitcnt vmcnt(11)
	ds_write2_b32 v82, v22, v23 offset1:1
	ds_write2_b32 v83, v24, v25 offset1:1
	s_waitcnt vmcnt(10)
	ds_write2_b32 v84, v18, v19 offset1:1
	ds_write2_b32 v85, v20, v21 offset1:1
	s_waitcnt vmcnt(9)
	ds_write2_b32 v86, v30, v31 offset1:1
	ds_write2_b32 v87, v32, v33 offset1:1
	s_waitcnt vmcnt(8)
	ds_write2_b32 v88, v26, v27 offset1:1
	ds_write2_b32 v89, v28, v29 offset1:1
	s_mul_hi_i32 s2, s14, 0x2fa0be83
	s_waitcnt lgkmcnt(0)
	s_lshr_b32 s3, s2, 31
	s_ashr_i32 s2, s2, 7
	s_add_i32 s20, s2, s3
	ds_read2_b32 v[6:7], v73 offset0:33 offset1:41
	ds_read2_b32 v[8:9], v73 offset1:8
	ds_read2_b32 v[10:11], v73 offset0:66 offset1:74
	ds_read2_b32 v[12:13], v73 offset0:99 offset1:107
	ds_read2_b32 v[14:15], v73 offset0:132 offset1:140
	ds_read2_b32 v[16:17], v73 offset0:165 offset1:173
	ds_read2_b32 v[18:19], v73 offset0:198 offset1:206
	ds_read2_b32 v[20:21], v73 offset0:231 offset1:239
	s_lshl_b32 s2, s20, 6
	s_mulk_i32 s20, 0xaa00
	v_add_u32_e32 v24, s20, v75
	s_ashr_i32 s3, s2, 31
	v_ashrrev_i32_e32 v25, 31, v24
	v_lshl_add_u64 v[22:23], s[2:3], 1, v[68:69]
	v_lshlrev_b64 v[26:27], 13, v[24:25]
	s_waitcnt lgkmcnt(6)
	v_cvt_pk_bf16_f32 v2, v8, v6
	s_waitcnt lgkmcnt(4)
	v_cvt_pk_bf16_f32 v3, v10, v12
	s_waitcnt lgkmcnt(2)
	v_cvt_pk_bf16_f32 v4, v14, v16
	s_waitcnt lgkmcnt(0)
	v_cvt_pk_bf16_f32 v5, v18, v20
	v_lshl_add_u64 v[26:27], v[22:23], 0, v[26:27]
	v_add_u32_e32 v6, 8, v24
	global_store_dwordx4 v[26:27], v[2:5], off nt
	s_cmp_gt_i32 s14, 0x90ff
	v_readlane_b32 s37, v243, 34
	v_cvt_pk_bf16_f32 v2, v9, v7
	v_ashrrev_i32_e32 v7, 31, v6
	v_cvt_pk_bf16_f32 v3, v11, v13
	v_cvt_pk_bf16_f32 v4, v15, v17
	v_cvt_pk_bf16_f32 v5, v19, v21
	v_lshlrev_b64 v[6:7], 13, v[6:7]
	ds_read2_b32 v[8:9], v73 offset0:49 offset1:57
	ds_read2_b32 v[10:11], v73 offset0:16 offset1:24
	ds_read2_b32 v[12:13], v73 offset0:82 offset1:90
	ds_read2_b32 v[14:15], v73 offset0:115 offset1:123
	ds_read2_b32 v[16:17], v73 offset0:148 offset1:156
	ds_read2_b32 v[18:19], v73 offset0:181 offset1:189
	ds_read2_b32 v[20:21], v73 offset0:214 offset1:222
	ds_read2_b32 v[26:27], v73 offset0:247 offset1:255
	v_lshl_add_u64 v[6:7], v[22:23], 0, v[6:7]
	global_store_dwordx4 v[6:7], v[2:5], off nt
	v_add_u32_e32 v6, 16, v24
	v_ashrrev_i32_e32 v7, 31, v6
	v_lshlrev_b64 v[6:7], 13, v[6:7]
	s_waitcnt lgkmcnt(6)
	v_cvt_pk_bf16_f32 v2, v10, v8
	s_waitcnt lgkmcnt(4)
	v_cvt_pk_bf16_f32 v3, v12, v14
	s_waitcnt lgkmcnt(2)
	v_cvt_pk_bf16_f32 v4, v16, v18
	s_waitcnt lgkmcnt(0)
	v_cvt_pk_bf16_f32 v5, v20, v26
	v_lshl_add_u64 v[6:7], v[22:23], 0, v[6:7]
	global_store_dwordx4 v[6:7], v[2:5], off nt
	v_add_u32_e32 v6, 24, v24
	v_ashrrev_i32_e32 v7, 31, v6
	v_lshlrev_b64 v[6:7], 13, v[6:7]
	v_cvt_pk_bf16_f32 v2, v11, v9
	v_cvt_pk_bf16_f32 v3, v13, v15
	v_cvt_pk_bf16_f32 v4, v17, v19
	v_cvt_pk_bf16_f32 v5, v21, v27
	v_lshl_add_u64 v[6:7], v[22:23], 0, v[6:7]
	global_store_dwordx4 v[6:7], v[2:5], off nt
	s_waitcnt lgkmcnt(0)
	v_readlane_b32 s38, v243, 35
	v_readlane_b32 s39, v243, 36
	v_readlane_b32 s40, v243, 37
	v_readlane_b32 s41, v243, 38
	v_readlane_b32 s42, v243, 39
	v_readlane_b32 s43, v243, 40
	v_readlane_b32 s44, v243, 41
	v_readlane_b32 s45, v243, 42
	v_readlane_b32 s48, v243, 45
	v_readlane_b32 s49, v243, 46
	v_readlane_b32 s50, v243, 47
	v_readlane_b32 s51, v243, 48
	s_cbranch_scc0 .LBB0_516
